# prep item assignment for all layers: 4 slots per block, [DFT,DFT,-,-] on 64 blocks and [DFT,light,light,light] on 192 (layers 0-2); last layer as before (no context DFT items, one latent DFT per block
# baseline (speedup 1.0000x reference)
; __device__ __forceinline__ int opaque_tid() { int t = threadIdx.x; asm volatile("" : "+v"(t)); return t; }
; __device__ __forceinline__ void phase_prep(const Params& P, int l, unsigned char* lds) {
;     ...
;     for (int item = blockIdx.x; item < ROWS / 64 + NBATCH * 20; item += G) {
;         const int tid = opaque_tid();
;         const int type = item >= ROWS / 64;
;         int r0, b, t0;
;         if (!type) { r0 = item * 64; b = r0 / TT; t0 = r0 - b * TT; }
;         else { const int idx = item - ROWS / 64; b = idx / 20; const int jb = idx - b * 20; t0 = (jb < 4) ? 64 * jb : CTX + 64 * (jb - 4); r0 = b * TT + t0; }
.LBB0_227:
	s_add_i32 s28, s28, s60
	s_cmpk_lt_i32 s28, 0x400
	s_cbranch_scc0 .LBB0_294
.LBB0_228:
	s_mov_b32 s101, s28
	s_cmp_lg_u32 s60, 0x100
	s_cbranch_scc1 .Lprep_map_done
	s_and_b32 s100, s28, 0xff
	s_lshr_b32 s101, s28, 8
	v_readlane_b32 vcc_lo, v255, 0
	s_nop 3
	s_cmp_eq_u32 vcc_lo, 3
	s_cbranch_scc1 .Lprep_last
	s_cmp_eq_u32 s101, 0
	s_cbranch_scc1 .Lprep_a0
	s_cmp_lt_u32 s100, 0x40
	s_cbranch_scc1 .Lprep_alo
	s_sub_u32 s101, s101, 1
	s_mul_i32 s101, s101, 0xc0
	s_add_u32 s101, s101, s100
	s_sub_u32 s101, s101, 0x40
	s_branch .Lprep_map_done
.Lprep_alo:
	s_cmp_eq_u32 s101, 1
	s_cbranch_scc0 .LBB0_227
	s_add_u32 s101, s100, 0x340
	s_branch .Lprep_map_done
.Lprep_a0:
	s_add_u32 s101, s100, 0x240
	s_branch .Lprep_map_done
.Lprep_last:
	s_cmp_eq_u32 s101, 0
	s_cbranch_scc1 .Lprep_k0
	s_cmp_eq_u32 s101, 3
	s_cbranch_scc1 .Lprep_k3
	s_sub_u32 s101, s101, 1
	s_lshl_b32 s101, s101, 8
	s_add_u32 s101, s101, s100
	s_branch .Lprep_map_done

; __device__ __forceinline__ int opaque_tid() { int t = threadIdx.x; asm volatile("" : "+v"(t)); return t; }
; __device__ __forceinline__ void phase_prep(const Params& P, int l, unsigned char* lds) {
;     ...
;     for (int item = blockIdx.x; item < ROWS / 64 + NBATCH * 20; item += G) {
;         const int tid = opaque_tid();
;         const int type = item >= ROWS / 64;
;         int r0, b, t0;
;         if (!type) { r0 = item * 64; b = r0 / TT; t0 = r0 - b * TT; }
;         else { const int idx = item - ROWS / 64; b = idx / 20; const int jb = idx - b * 20; t0 = (jb < 4) ? 64 * jb : CTX + 64 * (jb - 4); r0 = b * TT + t0; }
;         const bool is_ctx = t0 < CTX;
.Lprep_map_done:
	s_cmpk_lt_i32 s101, 0x380
	s_cbranch_scc0 .LBB0_227
	s_cmpk_gt_i32 s101, 0x23f
	s_cselect_b64 s[38:39], -1, 0
	v_mov_b32_e32 v44, v200
	s_mov_b64 s[40:41], -1
	s_and_b64 vcc, exec, s[38:39]
	s_cbranch_vccz .LBB0_230
	s_add_i32 s12, s101, 0xfffffdc0
	s_mul_i32 s13, s12, 0xcccd
	s_lshr_b32 s36, s13, 20
	s_mul_i32 s13, s36, 0xffffffec
	s_add_i32 s13, s13, s12
	s_lshl_b32 s64, s13, 6
	s_mul_i32 s12, s36, 0x900
	s_add_i32 s29, s64, s12
	s_mov_b64 s[40:41], 0
